# final RMSNorm row loop de-serialised: next row loads issued before current stores, counted waits
# baseline (speedup 1.0000x reference)
; __global__ void __launch_bounds__(NTHREADS, 2) mk_fwd(Args a) {
;     ...
;         const float* ss6 = ssp + (size_t)6 * SSP_STRIDE;
;         const bool local = bst[3] != 0u; const int xq = (int)bar.x, rank = (int)bst[2], nl = G / 8;
;         const int fn_first = local ? xq * SEQ + rank * NWAVES : vcu * NWAVES, fn_stride = (local ? nl : G) * NWAVES, fn_end = local ? (xq + 1) * SEQ : M;
;         f32x4 gv[2][2];
; #pragma unroll
;         for (int p = 0; p < 2; ++p) { gv[p][0] = *(const f32x4*)(P.final_g + p * 512 + lane * 8); gv[p][1] = *(const f32x4*)(P.final_g + p * 512 + lane * 8 + 4); }
;         for (int m = fn_first + wave; m < fn_end; m += fn_stride) {
;             const float rs = row_rstd(ss6, m);
; #pragma unroll
;             for (int p = 0; p < 2; ++p) {
;                 const u32x4 w = *(const u32x4*)(xb + (size_t)m * D + p * 512 + lane * 8);
;                 const f32x4 v0 = (f32x4){__uint_as_float(w.x << 16), __uint_as_float(w.x & 0xffff0000u), __uint_as_float(w.y << 16), __uint_as_float(w.y & 0xffff0000u)};
;                 const f32x4 v1 = (f32x4){__uint_as_float(w.z << 16), __uint_as_float(w.z & 0xffff0000u), __uint_as_float(w.w << 16), __uint_as_float(w.w & 0xffff0000u)};
;                 float* o = P.out + (size_t)m * D + p * 512 + lane * 8;
;                 __builtin_nontemporal_store(v0 * rs * gv[p][0], (f32x4*)o); __builtin_nontemporal_store(v1 * rs * gv[p][1], (f32x4*)(o + 4));
;             }
;         }
.LBB0_319:
	s_add_i32 s0, 0, 0x23ffc
	v_mov_b32_e32 v0, s0
	s_add_i32 s0, 0, 0x23ff8
	v_mov_b32_e32 v1, s0
	ds_read_b32 v0, v0
	ds_read_b32 v1, v1
	v_readlane_b32 s1, v253, 47
	s_add_i32 s2, s1, 0x1000
	s_waitcnt lgkmcnt(0)
	v_readfirstlane_b32 s0, v1
	s_lshl_b32 s0, s0, 3
	s_add_i32 s3, s0, s1
	v_readfirstlane_b32 s0, v0
	s_cmp_eq_u32 s0, 0
	s_cselect_b64 vcc, -1, 0
	s_and_b64 s[0:1], vcc, exec
	v_readlane_b32 s0, v253, 41
	s_cselect_b32 s1, s0, s3
	s_cselect_b32 s6, 0x8000, s2
	v_readlane_b32 s2, v255, 25
	s_add_i32 s0, s1, s2
	s_cmp_lt_i32 s0, s6
	s_cbranch_scc0 .LBB0_322
	v_readlane_b32 s8, v253, 2
	v_lshlrev_b32_e32 v20, 5, v232
	v_readlane_b32 s12, v253, 6
	v_readlane_b32 s13, v253, 7
	s_nop 4
	global_load_dwordx4 v[0:3], v20, s[12:13] offset:16
	global_load_dwordx4 v[4:7], v20, s[12:13]
	global_load_dwordx4 v[8:11], v20, s[12:13] offset:2064
	global_load_dwordx4 v[12:15], v20, s[12:13] offset:2048
	s_mov_b64 s[4:5], s[12:13]
	v_readlane_b32 s14, v253, 8
	v_readlane_b32 s15, v253, 9
	v_readlane_b32 s16, v253, 10
	v_readlane_b32 s17, v253, 11
	v_readlane_b32 s18, v253, 12
	v_readlane_b32 s19, v253, 13
	v_readlane_b32 s20, v253, 14
	v_readlane_b32 s21, v253, 15
	v_readlane_b32 s22, v253, 16
	v_readlane_b32 s23, v253, 17
	s_ashr_i32 s3, s1, 31
	s_ashr_i32 s4, s2, 31
	s_add_u32 s2, s1, s2
	v_readlane_b32 s12, v253, 18
	v_readlane_b32 s9, v253, 3
	s_addc_u32 s3, s3, s4
	v_readlane_b32 s14, v253, 20
	v_readlane_b32 s15, v253, 21
	v_readlane_b32 s26, v253, 32
	v_readlane_b32 s27, v253, 33
	v_mov_b32_e32 v16, s90
	s_lshl_b64 s[4:5], s[2:3], 6
	s_lshl_b64 s[8:9], s[2:3], 12
	s_mov_b64 s[14:15], s[26:27]
	v_cndmask_b32_e32 v16, v233, v16, vcc
	s_add_u32 s8, s14, s8
	v_lshlrev_b32_e32 v16, 3, v16
	v_mov_b32_e32 v21, 0
	s_addc_u32 s9, s15, s9
	v_ashrrev_i32_e32 v17, 31, v16
	v_lshl_add_u64 v[20:21], s[8:9], 0, v[20:21]
	s_mov_b64 s[8:9], 0x810
	s_lshl_b64 s[2:3], s[2:3], 11
	v_lshlrev_b64 v[18:19], 6, v[16:17]
	v_lshl_add_u64 v[20:21], v[20:21], 0, s[8:9]
	v_lshlrev_b64 v[22:23], 12, v[16:17]
	v_lshl_or_b32 v24, v232, 4, s2
	v_mov_b32_e32 v25, s3
	v_lshlrev_b64 v[26:27], 11, v[16:17]
	s_mov_b64 s[2:3], 0
	v_mov_b64_e32 v[28:29], s[4:5]
	v_mov_b32_e32 v17, s0
	s_mov_b64 s[4:5], 0xc00000
	v_mov_b32_e32 v30, 0x358637bd
	s_mov_b32 s7, 0x800000
	s_mov_b32 s8, 0x6200000
	v_readlane_b32 s10, v253, 4
	v_readlane_b32 s11, v253, 5
	v_readlane_b32 s13, v253, 19
	v_readlane_b32 s16, v253, 22
	v_readlane_b32 s17, v253, 23
	v_readlane_b32 s18, v253, 24
	v_readlane_b32 s19, v253, 25
	v_readlane_b32 s20, v253, 26
	v_readlane_b32 s21, v253, 27
	v_readlane_b32 s22, v253, 28
	v_readlane_b32 s23, v253, 29
	v_readlane_b32 s24, v253, 30
	v_readlane_b32 s25, v253, 31
	s_mov_b32 s9, 0
	v_lshl_add_u64 v[52:53], s[88:89], 0, v[28:29]
	v_lshl_add_u64 v[56:57], s[88:89], 0, v[24:25]
	v_lshl_add_u64 v[52:53], v[52:53], 0, s[4:5]
	v_lshl_add_u64 v[56:57], v[56:57], 0, s[8:9]
	global_load_dwordx4 v[32:35], v[52:53], off offset:32
	global_load_dwordx4 v[36:39], v[52:53], off offset:16
	global_load_dwordx4 v[40:43], v[52:53], off
	global_load_dwordx4 v[44:47], v[52:53], off offset:48
	global_load_dwordx4 v[48:51], v[56:57], off
	global_load_dwordx4 v[60:63], v[56:57], off offset:1024
	s_waitcnt vmcnt(0)
.Lmy_fn_loop:
	v_pk_add_f32 v[38:39], v[42:43], v[38:39]
	v_pk_add_f32 v[36:37], v[40:41], v[36:37]
	v_pk_add_f32 v[34:35], v[34:35], v[46:47]
	v_pk_add_f32 v[32:33], v[32:33], v[44:45]
	v_pk_add_f32 v[34:35], v[38:39], v[34:35]
	v_pk_add_f32 v[32:33], v[36:37], v[32:33]
	v_lshlrev_b32_e32 v64, 16, v48
	v_pk_mov_b32 v[36:37], v[32:33], v[34:35] op_sel:[1,0]
	v_mov_b32_e32 v33, v35
	v_pk_add_f32 v[32:33], v[36:37], v[32:33]
	v_and_b32_e32 v65, 0xffff0000, v48
	v_add_f32_e32 v31, v32, v33
	v_fmamk_f32 v31, v31, 0x3a800000, v30
	v_mul_f32_e32 v32, 0x4b800000, v31
	v_cmp_gt_f32_e32 vcc, s7, v31
	v_lshlrev_b32_e32 v66, 16, v49
	v_and_b32_e32 v67, 0xffff0000, v49
	v_cndmask_b32_e32 v31, v31, v32, vcc
	v_rsq_f32_e32 v31, v31
	v_lshlrev_b32_e32 v68, 16, v50
	v_and_b32_e32 v69, 0xffff0000, v50
	v_lshlrev_b32_e32 v70, 16, v51
	v_mul_f32_e32 v32, 0x45800000, v31
	v_cndmask_b32_e32 v58, v31, v32, vcc
	v_and_b32_e32 v71, 0xffff0000, v51
	v_lshlrev_b32_e32 v72, 16, v60
	v_and_b32_e32 v73, 0xffff0000, v60
	v_lshlrev_b32_e32 v74, 16, v61
	v_and_b32_e32 v75, 0xffff0000, v61
	v_lshlrev_b32_e32 v76, 16, v62
	v_and_b32_e32 v77, 0xffff0000, v62
	v_lshlrev_b32_e32 v78, 16, v63
	v_and_b32_e32 v79, 0xffff0000, v63
	v_mov_b32_e32 v80, v20
	v_mov_b32_e32 v81, v21
	v_add_u32_e32 v17, v17, v16
	v_lshl_add_u64 v[28:29], v[28:29], 0, v[18:19]
	v_lshl_add_u64 v[24:25], v[24:25], 0, v[26:27]
	v_lshl_add_u64 v[20:21], v[20:21], 0, v[22:23]
	v_cmp_gt_i32_e32 vcc, s6, v17
	s_cbranch_vccz .Lmy_fn_nonext
	v_lshl_add_u64 v[52:53], s[88:89], 0, v[28:29]
	v_lshl_add_u64 v[56:57], s[88:89], 0, v[24:25]
	v_lshl_add_u64 v[52:53], v[52:53], 0, s[4:5]
	v_lshl_add_u64 v[56:57], v[56:57], 0, s[8:9]
	global_load_dwordx4 v[32:35], v[52:53], off offset:32
	global_load_dwordx4 v[36:39], v[52:53], off offset:16
	global_load_dwordx4 v[40:43], v[52:53], off
	global_load_dwordx4 v[44:47], v[52:53], off offset:48
	global_load_dwordx4 v[48:51], v[56:57], off
	global_load_dwordx4 v[60:63], v[56:57], off offset:1024
.Lmy_fn_nonext:
	v_pk_mul_f32 v[64:65], v[58:59], v[64:65] op_sel_hi:[0,1]
	v_pk_mul_f32 v[66:67], v[58:59], v[66:67] op_sel_hi:[0,1]
	v_pk_mul_f32 v[68:69], v[58:59], v[68:69] op_sel_hi:[0,1]
	v_pk_mul_f32 v[70:71], v[58:59], v[70:71] op_sel_hi:[0,1]
	v_pk_mul_f32 v[72:73], v[58:59], v[72:73] op_sel_hi:[0,1]
	v_pk_mul_f32 v[74:75], v[58:59], v[74:75] op_sel_hi:[0,1]
	v_pk_mul_f32 v[76:77], v[58:59], v[76:77] op_sel_hi:[0,1]
	v_pk_mul_f32 v[78:79], v[58:59], v[78:79] op_sel_hi:[0,1]
	v_pk_mul_f32 v[64:65], v[4:5], v[64:65]
	v_pk_mul_f32 v[66:67], v[6:7], v[66:67]
	v_pk_mul_f32 v[68:69], v[0:1], v[68:69]
	v_pk_mul_f32 v[70:71], v[2:3], v[70:71]
	v_pk_mul_f32 v[72:73], v[12:13], v[72:73]
	v_pk_mul_f32 v[74:75], v[14:15], v[74:75]
	v_pk_mul_f32 v[76:77], v[8:9], v[76:77]
	v_pk_mul_f32 v[78:79], v[10:11], v[78:79]
	global_store_dwordx4 v[80:81], v[64:67], off offset:-2064 nt
	global_store_dwordx4 v[80:81], v[68:71], off offset:-2048 nt
	global_store_dwordx4 v[80:81], v[72:75], off offset:-16 nt
	global_store_dwordx4 v[80:81], v[76:79], off nt
	s_cbranch_vccz .LBB0_322
	s_waitcnt vmcnt(4)
	s_branch .Lmy_fn_loop
